# window walk: scale-subtract fma pairs packed into v_pk_fma_f32 (7 pairs)
# baseline (speedup 1.0000x reference)
.LBB0_1413:
	v_mov_b32_e32 v66, v151
	s_nop 1
	v_permlane16_swap_b32_e32 v151, v66
	v_max_f32_e32 v66, v66, v66
	v_max_f32_e32 v67, v151, v151
	v_max_f32_e32 v66, v67, v66
	v_mov_b32_e32 v67, v66
	s_nop 1
	v_permlane32_swap_b32_e32 v66, v67
	v_max3_f32 v106, v127, v66, v67
	v_max_f32_e32 v67, 0xe0ad78ec, v106
	v_mov_b32_e32 v66, v14
	v_pk_mul_f32 v[66:67], v[66:67], s[70:71] op_sel_hi:[1,0]
	v_subrev_u32_e32 v184, s19, v171
	v_pk_fma_f32 v[0:1], v[0:1], s[70:71], v[66:67] op_sel:[0,0,1] op_sel_hi:[1,0,1] neg_lo:[0,0,1] neg_hi:[0,0,1]
	v_exp_f32_e32 v107, v0
	v_exp_f32_e32 v108, v1
	v_pk_fma_f32 v[2:3], v[2:3], s[70:71], v[66:67] op_sel:[0,0,1] op_sel_hi:[1,0,1] neg_lo:[0,0,1] neg_hi:[0,0,1]
	v_exp_f32_e32 v109, v2
	v_exp_f32_e32 v110, v3
	v_pk_fma_f32 v[4:5], v[4:5], s[70:71], v[66:67] op_sel:[0,0,1] op_sel_hi:[1,0,1] neg_lo:[0,0,1] neg_hi:[0,0,1]
	v_exp_f32_e32 v111, v4
	v_exp_f32_e32 v112, v5
	v_pk_fma_f32 v[6:7], v[6:7], s[70:71], v[66:67] op_sel:[0,0,1] op_sel_hi:[1,0,1] neg_lo:[0,0,1] neg_hi:[0,0,1]
	v_exp_f32_e32 v113, v6
	v_exp_f32_e32 v151, v7
	v_pk_fma_f32 v[8:9], v[8:9], s[70:71], v[66:67] op_sel:[0,0,1] op_sel_hi:[1,0,1] neg_lo:[0,0,1] neg_hi:[0,0,1]
	v_exp_f32_e32 v152, v8
	v_exp_f32_e32 v170, v9
	v_pk_fma_f32 v[10:11], v[10:11], s[70:71], v[66:67] op_sel:[0,0,1] op_sel_hi:[1,0,1] neg_lo:[0,0,1] neg_hi:[0,0,1]
	v_exp_f32_e32 v174, v10
	v_exp_f32_e32 v175, v11
	v_pk_fma_f32 v[12:13], v[12:13], s[70:71], v[66:67] op_sel:[0,0,1] op_sel_hi:[1,0,1] neg_lo:[0,0,1] neg_hi:[0,0,1]
	v_exp_f32_e32 v176, v12
	v_exp_f32_e32 v177, v13
	v_sub_f32_e32 v0, v66, v67
	v_exp_f32_e32 v182, v0
	v_fma_f32 v0, v15, s70, -v67
	v_exp_f32_e32 v183, v0
	v_mfma_f32_16x16x32_bf16 v[0:3], v[98:101], v[30:33], 0
	v_subrev_u32_e32 v15, s19, v121
	v_cmp_lt_i32_e32 vcc, -1, v184
	v_cmp_gt_i32_e64 s[4:5], 64, v15
	v_mfma_f32_16x16x32_bf16 v[98:101], v[102:105], v[34:37], v[0:3]
	s_and_b64 s[4:5], s[4:5], vcc
	v_cmp_lt_i32_e32 vcc, 0, v15
	v_cmp_gt_i32_e64 s[6:7], 63, v184
	v_mfma_f32_16x16x32_bf16 v[0:3], v[90:93], v[30:33], 0
	s_or_b64 s[6:7], vcc, s[6:7]
	s_and_b64 vcc, s[4:5], s[6:7]
	v_cvt_pk_bf16_f32 v70, v107, v108
	v_mfma_f32_16x16x32_bf16 v[90:93], v[94:97], v[34:37], v[0:3]
	v_cvt_pk_bf16_f32 v71, v109, v110
	v_cvt_pk_bf16_f32 v72, v111, v112
	v_cvt_pk_bf16_f32 v73, v113, v151
	v_mfma_f32_16x16x32_bf16 v[0:3], v[86:89], v[30:33], 0
	v_cvt_pk_bf16_f32 v66, v152, v170
	v_cvt_pk_bf16_f32 v67, v174, v175
	v_cvt_pk_bf16_f32 v68, v176, v177
	v_mfma_f32_16x16x32_bf16 v[82:85], v[82:85], v[34:37], v[0:3]
	v_cvt_pk_bf16_f32 v69, v182, v183
	v_mfma_f32_16x16x32_bf16 v[0:3], v[78:81], v[30:33], 0
	v_mfma_f32_16x16x32_bf16 v[74:77], v[74:77], v[34:37], v[0:3]
	s_cbranch_vccz .LBB0_1420
	v_cmp_lt_i32_e32 vcc, v153, v15
	v_cmp_gt_i32_e64 s[6:7], v153, v184
	s_or_b64 vcc, vcc, s[6:7]
	s_nop 2
	v_cndmask_b32_e32 v0, v98, v246, vcc
	v_cmp_lt_i32_e32 vcc, v154, v15
	v_cmp_ge_i32_e64 s[6:7], v153, v184
	s_or_b64 vcc, vcc, s[6:7]
	v_cndmask_b32_e32 v1, v99, v246, vcc
	v_cmp_lt_i32_e32 vcc, v155, v15
	v_cmp_gt_i32_e64 s[6:7], v155, v184
	s_or_b64 vcc, vcc, s[6:7]
	v_cndmask_b32_e32 v2, v100, v246, vcc
	v_cmp_lt_i32_e32 vcc, v156, v15
	v_cmp_gt_i32_e64 s[6:7], v156, v184
	s_or_b64 vcc, vcc, s[6:7]
	v_cndmask_b32_e32 v3, v101, v246, vcc
	v_cmp_lt_i32_e32 vcc, v158, v15
	v_cmp_gt_i32_e64 s[6:7], v158, v184
	v_max3_f32 v4, v0, s96, v1
	s_or_b64 vcc, vcc, s[6:7]
	v_max3_f32 v6, v4, v2, v3
	v_cndmask_b32_e32 v4, v90, v246, vcc
	v_cmp_lt_i32_e32 vcc, v159, v15
	v_cmp_gt_i32_e64 s[6:7], v159, v184
	s_or_b64 vcc, vcc, s[6:7]
	v_cndmask_b32_e32 v5, v91, v246, vcc
	v_cmp_lt_i32_e32 vcc, v160, v15
	v_cmp_gt_i32_e64 s[6:7], v160, v184
	s_or_b64 vcc, vcc, s[6:7]
	v_max3_f32 v8, v6, v4, v5
	v_cndmask_b32_e32 v6, v92, v246, vcc
	v_cmp_lt_i32_e32 vcc, v161, v15
	v_cmp_gt_i32_e64 s[6:7], v161, v184
	s_or_b64 vcc, vcc, s[6:7]
	v_cndmask_b32_e32 v7, v93, v246, vcc
	v_cmp_lt_i32_e32 vcc, v162, v15
	v_cmp_gt_i32_e64 s[6:7], v162, v184
	s_or_b64 vcc, vcc, s[6:7]
	v_max3_f32 v10, v8, v6, v7
	v_cndmask_b32_e32 v8, v82, v246, vcc
	v_cmp_lt_i32_e32 vcc, v163, v15
	v_cmp_gt_i32_e64 s[6:7], v163, v184
	s_or_b64 vcc, vcc, s[6:7]
	v_cndmask_b32_e32 v9, v83, v246, vcc
	v_cmp_lt_i32_e32 vcc, v164, v15
	v_cmp_gt_i32_e64 s[6:7], v164, v184
	s_or_b64 vcc, vcc, s[6:7]
	v_max3_f32 v12, v10, v8, v9
	v_cndmask_b32_e32 v10, v84, v246, vcc
	v_cmp_lt_i32_e32 vcc, v165, v15
	v_cmp_gt_i32_e64 s[6:7], v165, v184
	s_or_b64 vcc, vcc, s[6:7]
	v_cndmask_b32_e32 v11, v85, v246, vcc
	v_cmp_lt_i32_e32 vcc, v166, v15
	v_cmp_gt_i32_e64 s[6:7], v166, v184
	s_or_b64 vcc, vcc, s[6:7]
	v_max3_f32 v14, v12, v10, v11
	v_cndmask_b32_e32 v12, v74, v246, vcc
	v_cmp_lt_i32_e32 vcc, v167, v15
	v_cmp_gt_i32_e64 s[6:7], v167, v184
	s_or_b64 vcc, vcc, s[6:7]
	v_cndmask_b32_e32 v13, v75, v246, vcc
	v_cmp_lt_i32_e32 vcc, v168, v15
	v_cmp_gt_i32_e64 s[6:7], v168, v184
	s_or_b64 vcc, vcc, s[6:7]
	v_max3_f32 v78, v14, v12, v13
	v_cndmask_b32_e32 v14, v76, v246, vcc
	v_cmp_lt_i32_e32 vcc, v169, v15
	v_cmp_gt_i32_e64 s[6:7], v169, v184
	s_or_b64 vcc, vcc, s[6:7]
	v_cndmask_b32_e32 v15, v77, v246, vcc
	v_max3_f32 v78, v78, v14, v15
	s_cbranch_execnz .LBB0_1416
